# speedup vs baseline: 1.1351x; 1.0672x over previous
; __device__ __forceinline__ void sb_mfma(int zz, const Params& p, int bh, int qb, char* shm) {
;     ...
;   const int tq0 = qb * 256 + w * 32;
;   bf16x8 qf[2][2];
; #pragma unroll
;   for (int n = 0; n < 2; ++n)
; #pragma unroll
;     for (int ds = 0; ds < 2; ++ds)
;       qf[n][ds] = *(const bf16x8*)(base + (long)(tq0 + n * 16 + fr) * QKVW + 2304 + hh * 64 + ds * 32 + fq * 8);
;   f32x4 o[4][2];
; #pragma unroll
;   for (int m = 0; m < 4; ++m)
; #pragma unroll
;     for (int n = 0; n < 2; ++n) o[m][n] = f32x4{0.f, 0.f, 0.f, 0.f};
;   float R[2] = {0.f, 0.f};
;   const int nkt = (qb + 1) * 4;
;   const int skey = tid >> 3, sd8 = (tid & 7) * 8;
;   const int krow = perm_row64(skey);
;   const u16* gk = base + (long)skey * QKVW + 2688 + hh * 64 + sd8;
;   uint4 rk, rv;
;   __syncthreads();
;   {
;     const u16* kp = gk + (long)(nkt - 1) * 64 * QKVW;
;     rk = *(const uint4*)kp;
;     rv = *(const uint4*)(kp + 384);
;   }
;   {
;     *(uint4*)(Ks + krow * 72 + sd8) = rk;
;     u16* vb = Vt + skey;
;     unsigned vv[4] = {rv.x, rv.y, rv.z, rv.w};
; #pragma unroll
;     for (int i = 0; i < 8; ++i) vb[perm_row64(sd8 + i) * 72] = (u16)((i & 1) ? (vv[i >> 1] >> 16) : (vv[i >> 1] & 0xffffu));
;   }
;   __syncthreads();
;     ...
;     const int cur = (nkt - 1 - kt) & 1;
;     if (kt > 0) {
;       const u16* kp = gk + (long)(kt - 1) * 64 * QKVW;
;       rk = *(const uint4*)kp;
;       rv = *(const uint4*)(kp + 384);
;     }
;     const int kbase = kt * 64;
;     if (kbase <= tq0 + 31) {
.LBB0_702:
	s_bitcmp0_b32 s43, 0
	v_readlane_b32 s8, v253, 10
	s_cselect_b32 s7, s8, s42
	s_add_i32 s6, s7, s6
	s_cmpk_gt_i32 s6, 0x2ff
	v_readlane_b32 s9, v253, 11
	s_cbranch_scc1 .LBB0_701
	s_mul_hi_i32 s7, s6, 0x2aaaaaab
	s_lshr_b32 s8, s7, 31
	s_lshr_b32 s7, s7, 3
	s_add_i32 s7, s7, s8
	s_mul_i32 s7, s7, 48
	s_sub_i32 s7, s6, s7
	s_mul_hi_i32 s6, s6, 0xd5555555
	s_lshr_b32 s8, s6, 31
	s_ashr_i32 s6, s6, 3
	s_add_i32 s12, s6, s8
	s_bfe_i32 s6, s7, 0x80000
	s_mul_i32 s6, s6, 43
	s_bfe_u32 s8, s6, 0x1000f
	s_bfe_u32 s6, s6, 0x80008
	s_add_i32 s6, s6, s8
	s_mul_i32 s8, s6, 6
	s_sub_i32 s7, s7, s8
	s_bfe_i64 s[76:77], s[6:7], 0x80000
	s_add_i32 s13, s12, 15
	s_mul_i32 s6, s76, 0x2d00000
	s_sext_i32_i8 s8, s7
	s_mul_hi_i32 s7, s76, 0x2d00000
	s_add_u32 s6, s72, s6
	s_addc_u32 s7, s73, s7
	v_lshl_add_u32 v100, s13, 8, v104
	s_lshl_b32 s8, s8, 6
	v_or_b32_e32 v101, v100, v92
	s_ashr_i32 s9, s8, 31
	v_mov_b64_e32 v[10:11], s[6:7]
	s_movk_i32 s14, 0x2d00
	v_mad_i64_i32 v[2:3], s[10:11], v101, s14, v[10:11]
	s_lshl_b64 s[40:41], s[8:9], 1
	v_lshl_add_u64 v[2:3], v[2:3], 0, s[40:41]
	v_or_b32_e32 v12, 16, v101
	v_lshl_add_u64 v[2:3], v[2:3], 0, v[0:1]
	s_mov_b64 s[16:17], 0x1200
	s_movk_i32 s10, 0x1000
	v_mad_i64_i32 v[10:11], s[8:9], v12, s14, v[10:11]
	s_waitcnt vmcnt(5)
	v_lshl_add_u64 v[18:19], s[6:7], 0, v[90:91]
	v_lshl_add_u64 v[6:7], v[2:3], 0, s[16:17]
	v_add_co_u32_e32 v2, vcc, s10, v2
	v_lshl_add_u64 v[10:11], v[10:11], 0, s[40:41]
	v_lshl_add_u64 v[18:19], v[18:19], 0, s[40:41]
	v_lshlrev_b32_e32 v20, 1, v94
	v_mov_b32_e32 v21, v1
	v_addc_co_u32_e32 v3, vcc, 0, v3, vcc
	v_lshl_add_u64 v[10:11], v[10:11], 0, v[0:1]
	s_lshl_b32 s8, s13, 2
	v_lshl_add_u64 v[18:19], v[18:19], 0, v[20:21]
	s_mov_b64 s[6:7], 0x1500
	v_lshl_add_u64 v[14:15], v[10:11], 0, s[16:17]
	v_add_co_u32_e32 v10, vcc, s10, v10
	v_lshl_add_u64 v[102:103], v[18:19], 0, s[6:7]
	s_or_b32 s6, s8, 3
	v_addc_co_u32_e32 v11, vcc, 0, v11, vcc
	s_waitcnt vmcnt(4)
	v_mad_u64_u32 v[22:23], s[6:7], s6, v190, v[102:103]
	global_load_dwordx4 v[2:5], v[2:3], off offset:512
	s_nop 0
	global_load_dwordx4 v[6:9], v[6:7], off offset:64
	s_nop 0
	global_load_dwordx4 v[10:13], v[10:11], off offset:512
	s_nop 0
	global_load_dwordx4 v[14:17], v[14:15], off offset:64
	s_barrier
	global_load_dwordx4 v[18:21], v[22:23], off
	s_nop 0
	global_load_dwordx4 v[22:25], v[22:23], off offset:768
	v_mov_b32_e32 v30, v1
	v_mov_b32_e32 v31, v1
	v_mov_b32_e32 v32, v1
	v_mov_b32_e32 v33, v1
	v_mov_b64_e32 v[26:27], v[30:31]
	v_mov_b64_e32 v[40:41], v[32:33]
	v_mov_b64_e32 v[36:37], v[32:33]
	v_mov_b64_e32 v[48:49], v[32:33]
	v_mov_b64_e32 v[44:45], v[32:33]
	v_mov_b64_e32 v[52:53], v[32:33]
	s_lshl_b32 s6, s12, 2
	s_lshl_b32 s7, s12, 8
	v_mov_b64_e32 v[56:57], v[32:33]
	v_mov_b32_e32 v111, 0
	v_mov_b32_e32 v112, 0
	v_mov_b64_e32 v[28:29], v[32:33]
	v_mov_b64_e32 v[38:39], v[30:31]
	v_mov_b64_e32 v[34:35], v[30:31]
	v_mov_b64_e32 v[46:47], v[30:31]
	v_mov_b64_e32 v[42:43], v[30:31]
	v_mov_b64_e32 v[50:51], v[30:31]
	v_or_b32_e32 v113, 31, v100
	v_or_b32_e32 v114, v100, v110
	s_add_i32 s82, s6, 62
	s_add_i32 s83, s7, 0xfff
	v_mov_b64_e32 v[54:55], v[30:31]
	s_waitcnt vmcnt(1)
	ds_write_b128 v105, v[18:21]
	s_waitcnt vmcnt(0)
	ds_write_b16 v106, v22 offset:18432
	ds_write_b16_d16_hi v106, v22 offset:18576
	ds_write_b16 v106, v23 offset:18720
	ds_write_b16_d16_hi v106, v23 offset:18864
	ds_write_b16 v106, v24 offset:20736
	ds_write_b16_d16_hi v106, v24 offset:20880
	ds_write_b16 v106, v25 offset:21024
	ds_write_b16_d16_hi v106, v25 offset:21168
	v_and_b32_e32 v58, 15, v99
	v_lshlrev_b32_e32 v58, 2, v58
	ds_write_b32 v58, v1 offset:36864
	s_waitcnt lgkmcnt(0)
	s_barrier
	s_branch .LBB0_705
.LBB0_704:
	s_add_i32 s82, s82, -1
	s_sub_i32 s83, s83, 64
	s_cmp_lg_u32 s82, -2
	s_waitcnt lgkmcnt(0)
	s_barrier
	s_cbranch_scc0 .LBB0_700
	s_add_i32 s6, s82, 1
	s_and_b32 s6, s6, 1
	s_lshl_b32 s6, s6, 5
	v_and_b32_e32 v58, 7, v99
	v_lshl_add_u32 v58, v58, 2, s6
	ds_read_b32 v58, v58 offset:36864
	s_waitcnt lgkmcnt(0)
	v_cmp_ne_u32_e32 vcc, 0, v58
	s_cmp_eq_u64 vcc, exec
	s_cbranch_scc1 .LBB0_700

; __device__ __forceinline__ void sb_mfma(int zz, const Params& p, int bh, int qb, char* shm) {
;     ...
;       f32x4 z[4][2];
; #pragma unroll
;       for (int m = 0; m < 4; ++m)
; #pragma unroll
;         for (int n = 0; n < 2; ++n) z[m][n] = f32x4{0.f, 0.f, 0.f, 0.f};
; #pragma unroll
;       for (int ds = 0; ds < 2; ++ds) {
;         bf16x8 kf[4];
; #pragma unroll
;         for (int m = 0; m < 4; ++m) kf[m] = *(const bf16x8*)(ksb + (m * 16 + fr) * 72 + ds * 32 + fq * 8);
; #pragma unroll
;         for (int m = 0; m < 4; ++m)
; #pragma unroll
;           for (int n = 0; n < 2; ++n) z[m][n] = __builtin_amdgcn_mfma_f32_16x16x32_bf16(kf[m], qf[n][ds], z[m][n], 0, 0, 0);
;       }
;       const bool diag = (kbase + 63 >= tq0);
;       bf16x8 pa[2][2];
; #pragma unroll
;       for (int n = 0; n < 2; ++n) {
;         const int tq = tq0 + n * 16 + fr;
;         const int key0 = kbase + fq * 16;
;         float L[16], X[16];
;         float T = 0.f;
; #pragma unroll
;         for (int m = 0; m < 4; ++m)
; #pragma unroll
;           for (int j = 0; j < 4; ++j) {
;             const int i = m * 4 + j;
;             float z2 = z[m][n][j] * cs;
;             float e = __builtin_amdgcn_exp2f(z2);
;             float l2 = __builtin_amdgcn_logf(1.0f + e);
;             l2 = (z2 > 60.f) ? z2 : l2;
;             float Lv = -l2;
;             if (diag) Lv = (key0 + i < tq) ? Lv : 0.f;
;             L[i] = Lv;
;             X[i] = z2 - l2;
;             T += Lv;
;           }
;         float t1 = __shfl(T, lane + 16, 64), t2 = __shfl(T, lane + 32, 64), t3 = __shfl(T, lane + 48, 64);
;         float suf = ((fq < 3) ? t1 : 0.f) + ((fq < 2) ? t2 : 0.f) + ((fq < 1) ? t3 : 0.f);
;         float tot = T + __shfl_xor(T, 16, 64);
;         tot += __shfl_xor(tot, 32, 64);
;         float run = R[n] + suf;
;         float A[16];
; #pragma unroll
;         for (int i = 15; i >= 0; --i) {
;           float a = __builtin_amdgcn_exp2f(X[i] + run);
;           if (diag) a = (key0 + i < tq) ? a : 0.f;
;           A[i] = a;
;           run += L[i];
;         }
.Lsb_fast:
	v_max_f32_e32 v115, v111, v112
	v_cmp_gt_f32_e32 vcc, 0xc3200000, v115
	s_cmp_eq_u64 vcc, exec
	s_cbranch_scc0 .Lsb_fast_go
	s_and_b32 s6, s82, 1
	s_lshl_b32 s6, s6, 5
	v_lshrrev_b32_e32 v124, 6, v139
	v_lshl_add_u32 v124, v124, 2, s6
	v_mov_b32_e32 v115, 1
	ds_write_b32 v124, v115 offset:36864
	s_branch .LBB0_709
.Lsb_fast_go:
	s_xor_b32 s85, s84, 1
	s_mulk_i32 s85, 0x2400
	v_or_b32_e32 v115, s85, v98
	v_add_u32_e32 v115, v115, v125
	ds_read_b128 v[58:61], v115 offset:6912
	ds_read_b128 v[62:65], v115 offset:4608
	ds_read_b128 v[66:69], v115 offset:2304
	ds_read_b128 v[70:73], v115
	ds_read_b128 v[116:119], v115 offset:6976
	ds_read_b128 v[120:123], v115 offset:4672
	v_lshlrev_b32_e32 v131, 2, v107
	v_lshlrev_b32_e32 v133, 2, v108
	v_lshlrev_b32_e32 v134, 2, v99
	v_xor_b32_e32 v132, 0x80, v134
	v_xor_b32_e32 v134, 64, v134
	v_or_b32_e32 v124, s85, v109
	v_add_u32_e32 v124, v124, v125
	s_waitcnt lgkmcnt(5)
	v_mfma_f32_16x16x32_bf16 v[140:143], v[58:61], v[2:5], 0
	v_mfma_f32_16x16x32_bf16 v[74:77], v[58:61], v[10:13], 0
	ds_read_b128 v[58:61], v115 offset:2368
	s_waitcnt lgkmcnt(5)
	v_mfma_f32_16x16x32_bf16 v[144:147], v[62:65], v[2:5], 0
	v_mfma_f32_16x16x32_bf16 v[78:81], v[62:65], v[10:13], 0
	ds_read_b128 v[62:65], v115 offset:64
	s_waitcnt lgkmcnt(5)
	v_mfma_f32_16x16x32_bf16 v[148:151], v[66:69], v[2:5], 0
	v_mfma_f32_16x16x32_bf16 v[82:85], v[66:69], v[10:13], 0
	s_waitcnt lgkmcnt(4)
	v_mfma_f32_16x16x32_bf16 v[152:155], v[70:73], v[2:5], 0
	v_mfma_f32_16x16x32_bf16 v[86:89], v[70:73], v[10:13], 0
	s_waitcnt lgkmcnt(3)
	v_mfma_f32_16x16x32_bf16 v[140:143], v[116:119], v[6:9], v[140:143]
	v_mfma_f32_16x16x32_bf16 v[74:77], v[116:119], v[14:17], v[74:77]
	s_waitcnt lgkmcnt(2)
	v_mfma_f32_16x16x32_bf16 v[144:147], v[120:123], v[6:9], v[144:147]
	v_mfma_f32_16x16x32_bf16 v[78:81], v[120:123], v[14:17], v[78:81]
	s_waitcnt lgkmcnt(1)
	v_mfma_f32_16x16x32_bf16 v[148:151], v[58:61], v[6:9], v[148:151]
	v_mfma_f32_16x16x32_bf16 v[82:85], v[58:61], v[14:17], v[82:85]
	s_waitcnt lgkmcnt(0)
	v_mfma_f32_16x16x32_bf16 v[152:155], v[62:65], v[6:9], v[152:155]
	v_mfma_f32_16x16x32_bf16 v[86:89], v[62:65], v[14:17], v[86:89]
	ds_read_b128 v[58:61], v124 offset:18432
	ds_read_b128 v[62:65], v124 offset:20736
	ds_read_b128 v[66:69], v124 offset:23040
	ds_read_b128 v[70:73], v124 offset:25344
	v_mov_b32_e32 v136, 1.0
	v_mul_f32_e32 v143, s98, v143
	v_mul_f32_e32 v142, s98, v142
	v_mul_f32_e32 v141, s98, v141
	v_mul_f32_e32 v140, s98, v140
	v_exp_f32_e32 v143, v143
	v_exp_f32_e32 v142, v142
	v_exp_f32_e32 v141, v141
	v_exp_f32_e32 v140, v140
	v_add_f32_e32 v115, 1.0, v143
	v_add_f32_e32 v127, 1.0, v142
	v_add_f32_e32 v128, 1.0, v141
	v_add_f32_e32 v137, 1.0, v140
	v_rcp_f32_e32 v115, v115
	v_rcp_f32_e32 v127, v127
	v_rcp_f32_e32 v128, v128
	v_rcp_f32_e32 v137, v137
	v_mul_f32_e32 v126, v136, v115
	v_sub_f32_e32 v143, v136, v126
	v_mul_f32_e32 v136, v126, v127
	v_sub_f32_e32 v142, v126, v136
	v_mul_f32_e32 v126, v136, v128
	v_sub_f32_e32 v141, v136, v126
	v_mul_f32_e32 v136, v126, v137
	v_sub_f32_e32 v140, v126, v136
	v_mul_f32_e32 v147, s98, v147
	v_mul_f32_e32 v146, s98, v146
	v_mul_f32_e32 v145, s98, v145
	v_mul_f32_e32 v144, s98, v144
	v_exp_f32_e32 v147, v147
	v_exp_f32_e32 v146, v146
	v_exp_f32_e32 v145, v145
	v_exp_f32_e32 v144, v144
	v_add_f32_e32 v115, 1.0, v147
	v_add_f32_e32 v127, 1.0, v146
	v_add_f32_e32 v128, 1.0, v145
	v_add_f32_e32 v137, 1.0, v144
	v_rcp_f32_e32 v115, v115
	v_rcp_f32_e32 v127, v127
	v_rcp_f32_e32 v128, v128
	v_rcp_f32_e32 v137, v137
	v_mul_f32_e32 v126, v136, v115
	v_sub_f32_e32 v147, v136, v126
	v_mul_f32_e32 v136, v126, v127
	v_sub_f32_e32 v146, v126, v136
	v_mul_f32_e32 v126, v136, v128
	v_sub_f32_e32 v145, v136, v126
	v_mul_f32_e32 v136, v126, v137
	v_sub_f32_e32 v144, v126, v136
	v_mul_f32_e32 v151, s98, v151
	v_mul_f32_e32 v150, s98, v150
	v_mul_f32_e32 v149, s98, v149
	v_mul_f32_e32 v148, s98, v148
	v_exp_f32_e32 v151, v151
	v_exp_f32_e32 v150, v150
	v_exp_f32_e32 v149, v149
	v_exp_f32_e32 v148, v148
	v_add_f32_e32 v115, 1.0, v151
	v_add_f32_e32 v127, 1.0, v150
	v_add_f32_e32 v128, 1.0, v149
	v_add_f32_e32 v137, 1.0, v148
	v_rcp_f32_e32 v115, v115
	v_rcp_f32_e32 v127, v127
	v_rcp_f32_e32 v128, v128
	v_rcp_f32_e32 v137, v137
	v_mul_f32_e32 v126, v136, v115
	v_sub_f32_e32 v151, v136, v126
	v_mul_f32_e32 v136, v126, v127
	v_sub_f32_e32 v150, v126, v136
	v_mul_f32_e32 v126, v136, v128
	v_sub_f32_e32 v149, v136, v126
	v_mul_f32_e32 v136, v126, v137
	v_sub_f32_e32 v148, v126, v136
	v_mul_f32_e32 v155, s98, v155
	v_mul_f32_e32 v154, s98, v154
	v_mul_f32_e32 v153, s98, v153
	v_mul_f32_e32 v152, s98, v152
	v_exp_f32_e32 v155, v155
	v_exp_f32_e32 v154, v154
	v_exp_f32_e32 v153, v153
	v_exp_f32_e32 v152, v152
	v_add_f32_e32 v115, 1.0, v155
	v_add_f32_e32 v127, 1.0, v154
	v_add_f32_e32 v128, 1.0, v153
	v_add_f32_e32 v137, 1.0, v152
	v_rcp_f32_e32 v115, v115
	v_rcp_f32_e32 v127, v127
	v_rcp_f32_e32 v128, v128
	v_rcp_f32_e32 v137, v137
	v_mul_f32_e32 v126, v136, v115
	v_sub_f32_e32 v155, v136, v126
	v_mul_f32_e32 v136, v126, v127
	v_sub_f32_e32 v154, v126, v136
	v_mul_f32_e32 v126, v136, v128
	v_sub_f32_e32 v153, v136, v126
	v_mul_f32_e32 v136, v126, v137
	v_sub_f32_e32 v152, v126, v136
	ds_bpermute_b32 v116, v131, v136
	ds_bpermute_b32 v117, v132, v136
	ds_bpermute_b32 v118, v133, v136
	ds_bpermute_b32 v119, v134, v136
	v_mov_b32_e32 v138, 1.0
	v_mul_f32_e32 v77, s98, v77
	v_mul_f32_e32 v76, s98, v76
	v_mul_f32_e32 v75, s98, v75
	v_mul_f32_e32 v74, s98, v74
	v_exp_f32_e32 v77, v77
	v_exp_f32_e32 v76, v76
	v_exp_f32_e32 v75, v75
	v_exp_f32_e32 v74, v74
	v_add_f32_e32 v115, 1.0, v77
	v_add_f32_e32 v127, 1.0, v76
; __device__ __forceinline__ void sb_mfma(int zz, const Params& p, int bh, int qb, char* shm) {
;     ...
;         float t1 = __shfl(T, lane + 16, 64), t2 = __shfl(T, lane + 32, 64), t3 = __shfl(T, lane + 48, 64);
;         float suf = ((fq < 3) ? t1 : 0.f) + ((fq < 2) ? t2 : 0.f) + ((fq < 1) ? t3 : 0.f);
;         float tot = T + __shfl_xor(T, 16, 64);
;         tot += __shfl_xor(tot, 32, 64);
;         float run = R[n] + suf;
;         float A[16];
; #pragma unroll
;         for (int i = 15; i >= 0; --i) {
;           float a = __builtin_amdgcn_exp2f(X[i] + run);
;           if (diag) a = (key0 + i < tq) ? a : 0.f;
;           A[i] = a;
;           run += L[i];
;         }
;         R[n] += tot;
; #pragma unroll
;         for (int kk = 0; kk < 2; ++kk) {
;           union { bf16x8 v; unsigned u[4]; } cv;
; #pragma unroll
;           for (int c = 0; c < 4; ++c) cv.u[c] = pack2(A[kk * 8 + 2 * c], A[kk * 8 + 2 * c + 1]);
;           pa[n][kk] = cv.v;
;         }
;       }
; #pragma unroll
;       for (int kk = 0; kk < 2; ++kk) {
;         bf16x8 vf[4];
; #pragma unroll
;         for (int md = 0; md < 4; ++md) vf[md] = *(const bf16x8*)(vsb + (md * 16 + fr) * 72 + fq * 16 + kk * 8);
; #pragma unroll
;         for (int md = 0; md < 4; ++md)
; #pragma unroll
;           for (int n = 0; n < 2; ++n) o[md][n] = __builtin_amdgcn_mfma_f32_16x16x32_bf16(vf[md], pa[n][kk], o[md][n], 0, 0, 0);
;       }
	v_add_f32_e32 v128, 1.0, v75
	v_add_f32_e32 v137, 1.0, v74
	v_rcp_f32_e32 v115, v115
	v_rcp_f32_e32 v127, v127
	v_rcp_f32_e32 v128, v128
	v_rcp_f32_e32 v137, v137
	v_mul_f32_e32 v126, v138, v115
	v_sub_f32_e32 v77, v138, v126
	v_mul_f32_e32 v138, v126, v127
	v_sub_f32_e32 v76, v126, v138
	v_mul_f32_e32 v126, v138, v128
	v_sub_f32_e32 v75, v138, v126
	v_mul_f32_e32 v138, v126, v137
	v_sub_f32_e32 v74, v126, v138
	v_mul_f32_e32 v81, s98, v81
	v_mul_f32_e32 v80, s98, v80
	v_mul_f32_e32 v79, s98, v79
	v_mul_f32_e32 v78, s98, v78
	v_exp_f32_e32 v81, v81
	v_exp_f32_e32 v80, v80
	v_exp_f32_e32 v79, v79
	v_exp_f32_e32 v78, v78
	v_add_f32_e32 v115, 1.0, v81
	v_add_f32_e32 v127, 1.0, v80
	v_add_f32_e32 v128, 1.0, v79
	v_add_f32_e32 v137, 1.0, v78
	v_rcp_f32_e32 v115, v115
	v_rcp_f32_e32 v127, v127
	v_rcp_f32_e32 v128, v128
	v_rcp_f32_e32 v137, v137
	v_mul_f32_e32 v126, v138, v115
	v_sub_f32_e32 v81, v138, v126
	v_mul_f32_e32 v138, v126, v127
	v_sub_f32_e32 v80, v126, v138
	v_mul_f32_e32 v126, v138, v128
	v_sub_f32_e32 v79, v138, v126
	v_mul_f32_e32 v138, v126, v137
	v_sub_f32_e32 v78, v126, v138
	v_mul_f32_e32 v85, s98, v85
	v_mul_f32_e32 v84, s98, v84
	v_mul_f32_e32 v83, s98, v83
	v_mul_f32_e32 v82, s98, v82
	v_exp_f32_e32 v85, v85
	v_exp_f32_e32 v84, v84
	v_exp_f32_e32 v83, v83
	v_exp_f32_e32 v82, v82
	v_add_f32_e32 v115, 1.0, v85
	v_add_f32_e32 v127, 1.0, v84
	v_add_f32_e32 v128, 1.0, v83
	v_add_f32_e32 v137, 1.0, v82
	v_rcp_f32_e32 v115, v115
	v_rcp_f32_e32 v127, v127
	v_rcp_f32_e32 v128, v128
	v_rcp_f32_e32 v137, v137
	v_mul_f32_e32 v126, v138, v115
	v_sub_f32_e32 v85, v138, v126
	v_mul_f32_e32 v138, v126, v127
	v_sub_f32_e32 v84, v126, v138
	v_mul_f32_e32 v126, v138, v128
	v_sub_f32_e32 v83, v138, v126
	v_mul_f32_e32 v138, v126, v137
	v_sub_f32_e32 v82, v126, v138
	v_mul_f32_e32 v89, s98, v89
	v_mul_f32_e32 v88, s98, v88
	v_mul_f32_e32 v87, s98, v87
	v_mul_f32_e32 v86, s98, v86
	v_exp_f32_e32 v89, v89
	v_exp_f32_e32 v88, v88
	v_exp_f32_e32 v87, v87
	v_exp_f32_e32 v86, v86
	v_add_f32_e32 v115, 1.0, v89
	v_add_f32_e32 v127, 1.0, v88
	v_add_f32_e32 v128, 1.0, v87
	v_add_f32_e32 v137, 1.0, v86
	v_rcp_f32_e32 v115, v115
	v_rcp_f32_e32 v127, v127
	v_rcp_f32_e32 v128, v128
	v_rcp_f32_e32 v137, v137
	v_mul_f32_e32 v126, v138, v115
	v_sub_f32_e32 v89, v138, v126
	v_mul_f32_e32 v138, v126, v127
	v_sub_f32_e32 v88, v126, v138
	v_mul_f32_e32 v126, v138, v128
	v_sub_f32_e32 v87, v138, v126
	v_mul_f32_e32 v138, v126, v137
	v_sub_f32_e32 v86, v126, v138
	ds_bpermute_b32 v156, v131, v138
	ds_bpermute_b32 v157, v132, v138
	ds_bpermute_b32 v158, v133, v138
	ds_bpermute_b32 v159, v134, v138
	v_exp_f32_e32 v122, v111
	v_exp_f32_e32 v123, v112
	s_waitcnt lgkmcnt(4)
	v_cndmask_b32_e64 v116, v116, 1.0, s[0:1]
	v_cndmask_b32_e64 v117, 1.0, v117, s[2:3]
	v_cndmask_b32_e64 v118, 1.0, v118, s[4:5]
	v_mul_f32_e32 v119, v136, v119
	ds_bpermute_b32 v120, v132, v119
	v_mul_f32_e32 v116, v116, v117
	v_mul_f32_e32 v116, v116, v118
	v_mul_f32_e32 v122, v122, v116
	v_mul_f32_e32 v140, v140, v122
	v_mul_f32_e32 v141, v141, v122
	v_mul_f32_e32 v142, v142, v122
	v_mul_f32_e32 v143, v143, v122
	v_mul_f32_e32 v144, v144, v122
	v_mul_f32_e32 v145, v145, v122
	v_mul_f32_e32 v146, v146, v122
	v_mul_f32_e32 v147, v147, v122
	v_mul_f32_e32 v148, v148, v122
	v_mul_f32_e32 v149, v149, v122
	v_mul_f32_e32 v150, v150, v122
	v_mul_f32_e32 v151, v151, v122
	v_mul_f32_e32 v152, v152, v122
	v_mul_f32_e32 v153, v153, v122
	v_mul_f32_e32 v154, v154, v122
	v_mul_f32_e32 v155, v155, v122
	v_cvt_pk_bf16_f32 v152, v152, v153
	v_cvt_pk_bf16_f32 v153, v154, v155
	v_cvt_pk_bf16_f32 v154, v148, v149
	v_cvt_pk_bf16_f32 v155, v150, v151
	v_cvt_pk_bf16_f32 v144, v144, v145
	v_cvt_pk_bf16_f32 v145, v146, v147
	v_cvt_pk_bf16_f32 v146, v140, v141
	v_cvt_pk_bf16_f32 v147, v142, v143
	s_waitcnt lgkmcnt(1)
	v_cndmask_b32_e64 v156, v156, 1.0, s[0:1]
	v_cndmask_b32_e64 v157, 1.0, v157, s[2:3]
	v_cndmask_b32_e64 v158, 1.0, v158, s[4:5]
	v_mul_f32_e32 v159, v138, v159
	ds_bpermute_b32 v121, v132, v159
	v_mul_f32_e32 v156, v156, v157
	v_mul_f32_e32 v156, v156, v158
	v_mul_f32_e32 v123, v123, v156
	s_waitcnt lgkmcnt(1)
	v_mul_f32_e32 v120, v119, v120
	v_log_f32_e32 v120, v120
	v_mul_f32_e32 v74, v74, v123
	v_mul_f32_e32 v75, v75, v123
	v_mul_f32_e32 v76, v76, v123
	v_mul_f32_e32 v77, v77, v123
	v_mul_f32_e32 v78, v78, v123
	v_mul_f32_e32 v79, v79, v123
	v_mul_f32_e32 v80, v80, v123
	v_mul_f32_e32 v81, v81, v123
	v_mul_f32_e32 v82, v82, v123
	v_mul_f32_e32 v83, v83, v123
	v_mul_f32_e32 v84, v84, v123
	v_mul_f32_e32 v85, v85, v123
	v_mul_f32_e32 v86, v86, v123
	v_mul_f32_e32 v87, v87, v123
	v_mul_f32_e32 v88, v88, v123
	v_mul_f32_e32 v89, v89, v123
	v_add_f32_e32 v111, v111, v120
	v_cvt_pk_bf16_f32 v86, v86, v87
	v_cvt_pk_bf16_f32 v87, v88, v89
	v_cvt_pk_bf16_f32 v88, v82, v83
	v_cvt_pk_bf16_f32 v89, v84, v85
	v_cvt_pk_bf16_f32 v78, v78, v79
	v_cvt_pk_bf16_f32 v79, v80, v81
	v_cvt_pk_bf16_f32 v80, v74, v75
	v_cvt_pk_bf16_f32 v81, v76, v77
	s_waitcnt lgkmcnt(0)
	v_mul_f32_e32 v121, v159, v121
	v_log_f32_e32 v121, v121
	ds_read_b128 v[116:119], v124 offset:18448
	ds_read_b128 v[140:143], v124 offset:25360
	v_add_f32_e32 v112, v112, v121
	ds_read_b128 v[120:123], v124 offset:20752
	ds_read_b128 v[156:159], v124 offset:23056
	v_mfma_f32_16x16x32_bf16 v[30:33], v[58:61], v[152:155], v[30:33]
	v_mfma_f32_16x16x32_bf16 v[26:29], v[58:61], v[86:89], v[26:29]
	v_mfma_f32_16x16x32_bf16 v[38:41], v[62:65], v[152:155], v[38:41]
	v_mfma_f32_16x16x32_bf16 v[34:37], v[62:65], v[86:89], v[34:37]
	v_mfma_f32_16x16x32_bf16 v[46:49], v[66:69], v[152:155], v[46:49]
	v_mfma_f32_16x16x32_bf16 v[42:45], v[66:69], v[86:89], v[42:45]
	v_mfma_f32_16x16x32_bf16 v[50:53], v[70:73], v[152:155], v[50:53]
	v_mfma_f32_16x16x32_bf16 v[54:57], v[70:73], v[86:89], v[54:57]
	s_waitcnt lgkmcnt(3)
	v_mfma_f32_16x16x32_bf16 v[30:33], v[116:119], v[144:147], v[30:33]
	v_mfma_f32_16x16x32_bf16 v[26:29], v[116:119], v[78:81], v[26:29]
	s_waitcnt lgkmcnt(2)
	v_mfma_f32_16x16x32_bf16 v[50:53], v[140:143], v[144:147], v[50:53]
	v_mfma_f32_16x16x32_bf16 v[54:57], v[140:143], v[78:81], v[54:57]
	s_waitcnt lgkmcnt(1)
	v_mfma_f32_16x16x32_bf16 v[38:41], v[120:123], v[144:147], v[38:41]
	v_mfma_f32_16x16x32_bf16 v[34:37], v[120:123], v[78:81], v[34:37]
	s_waitcnt lgkmcnt(0)
	v_mfma_f32_16x16x32_bf16 v[46:49], v[156:159], v[144:147], v[46:49]
	v_mfma_f32_16x16x32_bf16 v[42:45], v[156:159], v[78:81], v[42:45]
	s_branch .LBB0_709

; #define WAIT_V0() asm volatile("s_waitcnt vmcnt(0)" ::: "memory")
; template <int MF, int NF>
; __device__ __forceinline__ void gemm_main(int zz, f32x4 (&acc)[MF][NF], const u16* __restrict__ Wt, int ldw,
;                                           const u16* __restrict__ Act, int lda, int K, char* shm) {
;     ...
;   for (int t = 0; t < nt; ++t) {
;     const int cur = t & 1;
;     if (t + 1 < nt) {
; #pragma unroll
;       for (int i = 0; i < NLD; ++i) {
;         const u16* src = (i < NLA) ? (Wt + (long)(i * 64) * ldw + (t + 1) * 64 + voffA)
;                                    : (Act + (long)((i - NLA) * 64) * lda + (t + 1) * 64 + voffB);
;         __builtin_amdgcn_global_load_lds((const unsigned*)src, (unsigned*)(shm + (cur ^ 1) * STAGE_B + (i * 8 + wid) * 1024), 16, 0, 0);
;       }
;     }
;     const char* sbase = shm + cur * STAGE_B;
;     {
;       constexpr int D = (NF >= 4) ? 3 : ((MF >= 12) ? 6 : 4), RING = D + 1, NSTEP = 2 * MF;
;       bf16x8 Bf[2][NF], Ar[RING];
; #pragma unroll
;       for (int n = 0; n < NF; ++n) Bf[0][n] = *(const bf16x8*)(sbase + boff + (n * 2 + 0) * 1024);
; #pragma unroll
;       for (int j = 0; j < D; ++j) Ar[j % RING] = *(const bf16x8*)(sbase + aoff + ((j % MF) * 2 + (j / MF)) * 1024);
;       __builtin_amdgcn_sched_barrier(0);
;       __builtin_amdgcn_s_setprio(1);
; #pragma unroll
;       for (int i = 0; i < NSTEP; ++i) {
;         const int ks = i / MF, m = i % MF;
;         const int j = i + D;
;         if (j < NSTEP) {
;           const int ksj = j / MF, mj = j % MF;
;           if (mj == 0) {
; #pragma unroll
;             for (int n = 0; n < NF; ++n) Bf[ksj][n] = *(const bf16x8*)(sbase + boff + (n * 2 + ksj) * 1024);
;           }
;           Ar[j % RING] = *(const bf16x8*)(sbase + aoff + (mj * 2 + ksj) * 1024);
;         }
; #pragma unroll
;         for (int n = 0; n < NF; ++n) acc[m][n] = __builtin_amdgcn_mfma_f32_16x16x32_bf16(Ar[i % RING], Bf[ks][n], acc[m][n], 0, 0, 0);
;         __builtin_amdgcn_sched_barrier(0);
;       }
;       __builtin_amdgcn_s_setprio(0);
;     }
;     WAIT_V0();
;     __syncthreads();
.LBB0_755:
	s_and_b32 s12, s7, 0x10000
	s_xor_b32 s8, s12, 0x10000
	s_add_i32 s8, s8, s44
	s_mov_b32 m0, s8
	v_or_b32_e32 v0, s12, v122
	v_add_u32_e32 v133, v0, v124
	v_add_u32_e32 v0, v0, v123
	ds_read_b128 v[134:137], v133 offset:49152
	ds_read_b128 v[138:141], v133 offset:51200
	ds_read_b128 v[142:145], v0
	ds_read_b128 v[146:149], v0 offset:2048
	ds_read_b128 v[150:153], v0 offset:4096
	ds_read_b128 v[154:157], v0 offset:6144
	ds_read_b128 v[158:161], v0 offset:8192
	ds_read_b128 v[162:165], v0 offset:10240
	s_nop 0
	s_waitcnt lgkmcnt(5)
	v_mfma_f32_16x16x32_bf16 v[2:5], v[142:145], v[134:137], v[2:5]
	ds_read_b128 v[166:169], v0 offset:12288
	v_mfma_f32_16x16x32_bf16 v[6:9], v[142:145], v[138:141], v[6:9]
	global_load_lds_dwordx4 v212, s[40:41]
	s_waitcnt lgkmcnt(5)
	v_mfma_f32_16x16x32_bf16 v[10:13], v[146:149], v[134:137], v[10:13]
	s_add_u32 s40, s40, 0x20000
	s_addc_u32 s41, s41, 0
	s_addk_i32 m0, 0x2000
	ds_read_b128 v[142:145], v0 offset:14336
	v_mfma_f32_16x16x32_bf16 v[14:17], v[146:149], v[138:141], v[14:17]
	s_waitcnt lgkmcnt(5)
	v_mfma_f32_16x16x32_bf16 v[18:21], v[150:153], v[134:137], v[18:21]
	global_load_lds_dwordx4 v212, s[40:41]
	ds_read_b128 v[146:149], v0 offset:16384
	v_mfma_f32_16x16x32_bf16 v[22:25], v[150:153], v[138:141], v[22:25]
	s_add_u32 s40, s40, 0x20000
	s_addc_u32 s41, s41, 0
	s_addk_i32 m0, 0x2000
	s_waitcnt lgkmcnt(5)
	v_mfma_f32_16x16x32_bf16 v[26:29], v[154:157], v[134:137], v[26:29]
	ds_read_b128 v[150:153], v0 offset:18432
	v_mfma_f32_16x16x32_bf16 v[38:41], v[154:157], v[138:141], v[38:41]
	global_load_lds_dwordx4 v212, s[40:41]
	s_waitcnt lgkmcnt(5)
	v_mfma_f32_16x16x32_bf16 v[50:53], v[158:161], v[134:137], v[50:53]
	s_add_u32 s40, s40, 0x20000
	s_addc_u32 s41, s41, 0
	s_addk_i32 m0, 0x2000
	ds_read_b128 v[154:157], v0 offset:20480
	v_mfma_f32_16x16x32_bf16 v[74:77], v[158:161], v[138:141], v[74:77]
	s_waitcnt lgkmcnt(5)
	v_mfma_f32_16x16x32_bf16 v[86:89], v[162:165], v[134:137], v[86:89]
	global_load_lds_dwordx4 v212, s[40:41]
	ds_read_b128 v[158:161], v0 offset:22528
	v_mfma_f32_16x16x32_bf16 v[94:97], v[162:165], v[138:141], v[94:97]
	s_add_u32 s40, s40, 0x20000
	s_addc_u32 s41, s41, 0
	s_addk_i32 m0, 0x2000
	ds_read_b128 v[162:165], v133 offset:50176
	ds_read_b128 v[170:173], v133 offset:52224
	ds_read_b128 v[174:177], v0 offset:1024
	s_waitcnt lgkmcnt(8)
	v_mfma_f32_16x16x32_bf16 v[62:65], v[166:169], v[134:137], v[62:65]
	v_mfma_f32_16x16x32_bf16 v[30:33], v[166:169], v[138:141], v[30:33]
	global_load_lds_dwordx4 v212, s[40:41]
	s_waitcnt lgkmcnt(7)
	v_mfma_f32_16x16x32_bf16 v[34:37], v[142:145], v[134:137], v[34:37]
	s_add_u32 s40, s40, 0x20000
	s_addc_u32 s41, s41, 0
	s_addk_i32 m0, 0x2000
	ds_read_b128 v[166:169], v0 offset:3072
	v_mfma_f32_16x16x32_bf16 v[42:45], v[142:145], v[138:141], v[42:45]
	s_waitcnt lgkmcnt(7)
	v_mfma_f32_16x16x32_bf16 v[46:49], v[146:149], v[134:137], v[46:49]
	global_load_lds_dwordx4 v212, s[40:41]
	ds_read_b128 v[142:145], v0 offset:5120
	v_mfma_f32_16x16x32_bf16 v[54:57], v[146:149], v[138:141], v[54:57]
	s_add_u32 s40, s40, 0xfff60080
	s_addc_u32 s41, s41, -1
	s_addk_i32 m0, 0x2000
	s_waitcnt lgkmcnt(7)
	v_mfma_f32_16x16x32_bf16 v[58:61], v[150:153], v[134:137], v[58:61]
	ds_read_b128 v[146:149], v0 offset:7168
	v_mfma_f32_16x16x32_bf16 v[66:69], v[150:153], v[138:141], v[66:69]
	global_load_lds_dwordx4 v212, s[42:43]
	s_waitcnt lgkmcnt(7)
	v_mfma_f32_16x16x32_bf16 v[70:73], v[154:157], v[134:137], v[70:73]
	s_add_u32 s42, s42, 0x20000
	s_addc_u32 s43, s43, 0
	s_addk_i32 m0, 0x2000
	ds_read_b128 v[150:153], v0 offset:9216
	v_mfma_f32_16x16x32_bf16 v[78:81], v[154:157], v[138:141], v[78:81]
	s_waitcnt lgkmcnt(7)
	v_mfma_f32_16x16x32_bf16 v[82:85], v[158:161], v[134:137], v[82:85]
	global_load_lds_dwordx4 v212, s[42:43]
	ds_read_b128 v[134:137], v0 offset:11264
	v_mfma_f32_16x16x32_bf16 v[90:93], v[158:161], v[138:141], v[90:93]
	s_add_u32 s42, s42, 0xfffe0080
	s_addc_u32 s43, s43, -1
	s_waitcnt lgkmcnt(5)
	v_mfma_f32_16x16x32_bf16 v[2:5], v[174:177], v[162:165], v[2:5]
	ds_read_b128 v[138:141], v0 offset:13312
	v_mfma_f32_16x16x32_bf16 v[6:9], v[174:177], v[170:173], v[6:9]
	s_waitcnt lgkmcnt(5)
	v_mfma_f32_16x16x32_bf16 v[10:13], v[166:169], v[162:165], v[10:13]
	ds_read_b128 v[154:157], v0 offset:15360
	v_mfma_f32_16x16x32_bf16 v[14:17], v[166:169], v[170:173], v[14:17]
	s_waitcnt lgkmcnt(5)
	v_mfma_f32_16x16x32_bf16 v[18:21], v[142:145], v[162:165], v[18:21]
	ds_read_b128 v[158:161], v0 offset:17408
	v_mfma_f32_16x16x32_bf16 v[22:25], v[142:145], v[170:173], v[22:25]
	s_waitcnt lgkmcnt(5)
	v_mfma_f32_16x16x32_bf16 v[26:29], v[146:149], v[162:165], v[26:29]
	ds_read_b128 v[142:145], v0 offset:19456
	v_mfma_f32_16x16x32_bf16 v[38:41], v[146:149], v[170:173], v[38:41]
	s_waitcnt lgkmcnt(5)
	v_mfma_f32_16x16x32_bf16 v[50:53], v[150:153], v[162:165], v[50:53]
	ds_read_b128 v[146:149], v0 offset:21504
	v_mfma_f32_16x16x32_bf16 v[74:77], v[150:153], v[170:173], v[74:77]
	s_waitcnt lgkmcnt(5)
	v_mfma_f32_16x16x32_bf16 v[86:89], v[134:137], v[162:165], v[86:89]
	ds_read_b128 v[150:153], v0 offset:23552
	v_mfma_f32_16x16x32_bf16 v[94:97], v[134:137], v[170:173], v[94:97]
	s_waitcnt lgkmcnt(5)
	v_mfma_f32_16x16x32_bf16 v[62:65], v[138:141], v[162:165], v[62:65]
	v_mfma_f32_16x16x32_bf16 v[30:33], v[138:141], v[170:173], v[30:33]
	s_waitcnt lgkmcnt(4)
	v_mfma_f32_16x16x32_bf16 v[34:37], v[154:157], v[162:165], v[34:37]
	v_mfma_f32_16x16x32_bf16 v[42:45], v[154:157], v[170:173], v[42:45]
	s_waitcnt lgkmcnt(3)
	v_mfma_f32_16x16x32_bf16 v[46:49], v[158:161], v[162:165], v[46:49]
	v_mfma_f32_16x16x32_bf16 v[54:57], v[158:161], v[170:173], v[54:57]
	s_waitcnt lgkmcnt(2)
	v_mfma_f32_16x16x32_bf16 v[58:61], v[142:145], v[162:165], v[58:61]
	v_mfma_f32_16x16x32_bf16 v[66:69], v[142:145], v[170:173], v[66:69]
	s_waitcnt lgkmcnt(1)
	v_mfma_f32_16x16x32_bf16 v[70:73], v[146:149], v[162:165], v[70:73]
	v_mfma_f32_16x16x32_bf16 v[78:81], v[146:149], v[170:173], v[78:81]
	s_waitcnt lgkmcnt(0)
	v_mfma_f32_16x16x32_bf16 v[82:85], v[150:153], v[162:165], v[82:85]
	v_mfma_f32_16x16x32_bf16 v[90:93], v[150:153], v[170:173], v[90:93]
	s_nop 0
	s_add_i32 s7, s7, 0x10000
	s_waitcnt vmcnt(0)
	s_add_u32 s2, s2, 0x80
	s_addc_u32 s3, s3, 0
	s_cmpk_lg_i32 s2, 0x780
	s_waitcnt vmcnt(0)
	s_barrier
; __device__ __forceinline__ float sigmoid_fast(float x) { return __builtin_amdgcn_rcpf(1.0f + __expf(-x)); }
; template <int MF, int NF>
; __device__ __forceinline__ void gemm_main(int zz, f32x4 (&acc)[MF][NF], const u16* __restrict__ Wt, int ldw,
;                                           const u16* __restrict__ Act, int lda, int K, char* shm) {
;     ...
;     {
;       constexpr int D = (NF >= 4) ? 3 : ((MF >= 12) ? 6 : 4), RING = D + 1, NSTEP = 2 * MF;
;       bf16x8 Bf[2][NF], Ar[RING];
; #pragma unroll
;       for (int n = 0; n < NF; ++n) Bf[0][n] = *(const bf16x8*)(sbase + boff + (n * 2 + 0) * 1024);
; #pragma unroll
;       for (int j = 0; j < D; ++j) Ar[j % RING] = *(const bf16x8*)(sbase + aoff + ((j % MF) * 2 + (j / MF)) * 1024);
;       __builtin_amdgcn_sched_barrier(0);
;       __builtin_amdgcn_s_setprio(1);
; #pragma unroll
;       for (int i = 0; i < NSTEP; ++i) {
;         const int ks = i / MF, m = i % MF;
;         const int j = i + D;
;         if (j < NSTEP) {
;           const int ksj = j / MF, mj = j % MF;
;           if (mj == 0) {
; #pragma unroll
;             for (int n = 0; n < NF; ++n) Bf[ksj][n] = *(const bf16x8*)(sbase + boff + (n * 2 + ksj) * 1024);
;           }
;           Ar[j % RING] = *(const bf16x8*)(sbase + aoff + (mj * 2 + ksj) * 1024);
;         }
; #pragma unroll
;         for (int n = 0; n < NF; ++n) acc[m][n] = __builtin_amdgcn_mfma_f32_16x16x32_bf16(Ar[i % RING], Bf[ks][n], acc[m][n], 0, 0, 0);
;         __builtin_amdgcn_sched_barrier(0);
;       }
;       __builtin_amdgcn_s_setprio(0);
;     }
; __device__ __forceinline__ void g4_phase(int zz, const Params& p, char* shm) {
;     ...
;     gemm_issue_first<4, 2>(zz, p.W + OFF_WBA + (long)c0 * 1024, 1024, p.ymix + (long)t0 * 1024, 1024, shm);
;     unsigned gp[12][2][2];
; #pragma unroll
;     for (int m = 0; m < 12; ++m)
; #pragma unroll
;       for (int n = 0; n < 2; ++n) {
;         gp[m][n][0] = pack2(sigmoid_fast(g[m][n][0]), sigmoid_fast(g[m][n][1]));
;         gp[m][n][1] = pack2(sigmoid_fast(g[m][n][2]), sigmoid_fast(g[m][n][3]));
	s_cbranch_scc1 .LBB0_755
	ds_read_b128 v[110:113], v131 offset:10240
	ds_read_b128 v[134:137], v131 offset:8192
	ds_read_b128 v[138:141], v131 offset:6144
	ds_read_b128 v[142:145], v131 offset:4096
	ds_read_b128 v[146:149], v131 offset:2048
	ds_read_b128 v[150:153], v131
	ds_read_b128 v[154:157], v132 offset:51200
	ds_read_b128 v[158:161], v132 offset:49152
	s_setprio 1
	s_waitcnt lgkmcnt(0)
	v_mfma_f32_16x16x32_bf16 v[2:5], v[150:153], v[158:161], v[2:5]
	ds_read_b128 v[162:165], v131 offset:12288
	v_mfma_f32_16x16x32_bf16 v[6:9], v[150:153], v[154:157], v[6:9]
	ds_read_b128 v[150:153], v131 offset:14336
	v_mfma_f32_16x16x32_bf16 v[10:13], v[146:149], v[158:161], v[10:13]
	v_mfma_f32_16x16x32_bf16 v[14:17], v[146:149], v[154:157], v[14:17]
	ds_read_b128 v[146:149], v131 offset:16384
	v_mfma_f32_16x16x32_bf16 v[18:21], v[142:145], v[158:161], v[18:21]
	v_mfma_f32_16x16x32_bf16 v[22:25], v[142:145], v[154:157], v[22:25]
	ds_read_b128 v[142:145], v131 offset:18432
	v_mfma_f32_16x16x32_bf16 v[26:29], v[138:141], v[158:161], v[26:29]
	v_mfma_f32_16x16x32_bf16 v[38:41], v[138:141], v[154:157], v[38:41]
	ds_read_b128 v[138:141], v131 offset:20480
	v_mfma_f32_16x16x32_bf16 v[50:53], v[134:137], v[158:161], v[50:53]
	v_mfma_f32_16x16x32_bf16 v[74:77], v[134:137], v[154:157], v[74:77]
	ds_read_b128 v[134:137], v131 offset:22528
	v_mfma_f32_16x16x32_bf16 v[86:89], v[110:113], v[158:161], v[86:89]
	v_mfma_f32_16x16x32_bf16 v[94:97], v[110:113], v[154:157], v[94:97]
	s_waitcnt lgkmcnt(5)
	v_mfma_f32_16x16x32_bf16 v[110:113], v[162:165], v[158:161], v[62:65]
	ds_read_b128 v[166:169], v132 offset:52224
	ds_read_b128 v[170:173], v132 offset:50176
	s_nop 0
	ds_read_b128 v[62:65], v131 offset:1024
	v_mfma_f32_16x16x32_bf16 v[30:33], v[162:165], v[154:157], v[30:33]
	s_waitcnt lgkmcnt(7)
	v_mfma_f32_16x16x32_bf16 v[34:37], v[150:153], v[158:161], v[34:37]
	ds_read_b128 v[162:165], v131 offset:3072
	v_mfma_f32_16x16x32_bf16 v[150:153], v[150:153], v[154:157], v[42:45]
	s_nop 2
	ds_read_b128 v[42:45], v131 offset:5120
	s_waitcnt lgkmcnt(8)
	v_mfma_f32_16x16x32_bf16 v[174:177], v[146:149], v[158:161], v[46:49]
	v_mfma_f32_16x16x32_bf16 v[146:149], v[146:149], v[154:157], v[54:57]
	s_nop 1
	ds_read_b128 v[46:49], v131 offset:7168
	s_waitcnt lgkmcnt(8)
	v_mfma_f32_16x16x32_bf16 v[192:195], v[142:145], v[158:161], v[58:61]
	v_mfma_f32_16x16x32_bf16 v[142:145], v[142:145], v[154:157], v[66:69]
	ds_read_b128 v[54:57], v131 offset:9216
	s_waitcnt lgkmcnt(8)
	v_mfma_f32_16x16x32_bf16 v[70:73], v[138:141], v[158:161], v[70:73]
	v_mfma_f32_16x16x32_bf16 v[78:81], v[138:141], v[154:157], v[78:81]
	ds_read_b128 v[138:141], v131 offset:11264
	s_waitcnt lgkmcnt(8)
	v_mfma_f32_16x16x32_bf16 v[82:85], v[134:137], v[158:161], v[82:85]
	v_mfma_f32_16x16x32_bf16 v[90:93], v[134:137], v[154:157], v[90:93]
	s_waitcnt lgkmcnt(5)
	v_mfma_f32_16x16x32_bf16 v[134:137], v[62:65], v[170:173], v[2:5]
	s_nop 2
	ds_read_b128 v[2:5], v131 offset:13312
	v_mfma_f32_16x16x32_bf16 v[154:157], v[62:65], v[166:169], v[6:9]
	s_nop 2
	ds_read_b128 v[6:9], v131 offset:15360
	s_waitcnt lgkmcnt(6)
	v_mfma_f32_16x16x32_bf16 v[158:161], v[162:165], v[170:173], v[10:13]
	v_mfma_f32_16x16x32_bf16 v[162:165], v[162:165], v[166:169], v[14:17]
	s_nop 1
	ds_read_b128 v[10:13], v131 offset:17408
	s_waitcnt lgkmcnt(6)
	v_mfma_f32_16x16x32_bf16 v[196:199], v[42:45], v[170:173], v[18:21]
	v_mfma_f32_16x16x32_bf16 v[200:203], v[42:45], v[166:169], v[22:25]
	ds_read_b128 v[14:17], v131 offset:19456
	s_waitcnt lgkmcnt(6)
	v_mfma_f32_16x16x32_bf16 v[66:69], v[46:49], v[166:169], v[38:41]
	v_mfma_f32_16x16x32_bf16 v[204:207], v[46:49], v[170:173], v[26:29]
	s_waitcnt lgkmcnt(5)
	v_mfma_f32_16x16x32_bf16 v[62:65], v[54:57], v[170:173], v[50:53]
	ds_read_b128 v[208:211], v131 offset:21504
	v_mfma_f32_16x16x32_bf16 v[58:61], v[54:57], v[166:169], v[74:77]
	s_nop 2
	ds_read_b128 v[74:77], v131 offset:23552
	s_waitcnt lgkmcnt(6)
	v_mfma_f32_16x16x32_bf16 v[54:57], v[138:141], v[170:173], v[86:89]
	v_mfma_f32_16x16x32_bf16 v[50:53], v[138:141], v[166:169], v[94:97]
	s_waitcnt lgkmcnt(5)
	v_mfma_f32_16x16x32_bf16 v[46:49], v[2:5], v[170:173], v[110:113]
	v_mfma_f32_16x16x32_bf16 v[42:45], v[2:5], v[166:169], v[30:33]
	s_waitcnt lgkmcnt(4)
	v_mfma_f32_16x16x32_bf16 v[38:41], v[6:9], v[170:173], v[34:37]
	v_mfma_f32_16x16x32_bf16 v[34:37], v[6:9], v[166:169], v[150:153]
	s_waitcnt lgkmcnt(3)
	v_mfma_f32_16x16x32_bf16 v[30:33], v[10:13], v[170:173], v[174:177]
	v_mfma_f32_16x16x32_bf16 v[26:29], v[10:13], v[166:169], v[146:149]
	s_waitcnt lgkmcnt(2)
	v_mfma_f32_16x16x32_bf16 v[22:25], v[14:17], v[170:173], v[192:195]
	v_mfma_f32_16x16x32_bf16 v[18:21], v[14:17], v[166:169], v[142:145]
	s_waitcnt lgkmcnt(1)
	v_mfma_f32_16x16x32_bf16 v[14:17], v[208:211], v[170:173], v[70:73]
	v_mfma_f32_16x16x32_bf16 v[10:13], v[208:211], v[166:169], v[78:81]
	s_waitcnt lgkmcnt(0)
	v_mfma_f32_16x16x32_bf16 v[6:9], v[74:77], v[170:173], v[82:85]
	v_mfma_f32_16x16x32_bf16 v[2:5], v[74:77], v[166:169], v[90:93]
	s_setprio 0
	s_lshl_b32 s2, s6, 7
	s_ashr_i32 s3, s2, 31
	s_lshl_b64 s[6:7], s[2:3], 11
	v_readlane_b32 s8, v252, 35
	v_readlane_b32 s9, v252, 36
	s_add_u32 s8, s8, s6
	s_addc_u32 s9, s9, s7
	s_lshl_b64 s[12:13], s[0:1], 11
	v_readfirstlane_b32 s1, v114
	v_mul_f32_e32 v0, 0xbfb8aa3b, v134
	v_mul_f32_e32 v76, 0xbfb8aa3b, v135
	s_add_u32 s12, s70, s12
	v_lshl_add_u64 v[72:73], s[8:9], 0, v[98:99]
	s_mov_b32 m0, s1
	s_mov_b64 s[8:9], 0x20000
	v_readfirstlane_b32 s1, v115
	v_exp_f32_e32 v0, v0
	v_exp_f32_e32 v76, v76
	s_waitcnt vmcnt(0)
	s_barrier
; __device__ __forceinline__ float sigmoid_fast(float x) { return __builtin_amdgcn_rcpf(1.0f + __expf(-x)); }
; template <int MF, int NF>
; __device__ __forceinline__ void gemm_issue_first(int zz, const u16* __restrict__ Wt, int ldw, const u16* __restrict__ Act, int lda,
;                                                  char* shm) {
;   constexpr int TA = 32 * MF, TB = 64 * NF, NLD = (TA + TB) / 64, NLA = TA / 64;
;   const int tid = TIDX, wid = tid >> 6, lane = tid & 63;
;   const int sb = lane * 16;
;   const int swz = sb ^ (((sb >> 9) & 1) << 5);
;   const int rr = swz >> 6, cc = (swz & 63) >> 1;
;   const unsigned voffA = (unsigned)(((wid >> 1) * 16 + rr) * ldw + (wid & 1) * 32 + cc);
;   const unsigned voffB = (unsigned)(((wid >> 1) * 16 + rr) * lda + (wid & 1) * 32 + cc);
; #pragma unroll
;   for (int i = 0; i < NLD; ++i) {
;     const u16* src = (i < NLA) ? (Wt + (long)(i * 64) * ldw + voffA) : (Act + (long)((i - NLA) * 64) * lda + voffB);
;     __builtin_amdgcn_global_load_lds((const unsigned*)src, (unsigned*)(shm + (i * 8 + wid) * 1024), 16, 0, 0);
;   }
; __device__ __forceinline__ void g4_phase(int zz, const Params& p, char* shm) {
;     ...
;     unsigned gp[12][2][2];
; #pragma unroll
;     for (int m = 0; m < 12; ++m)
; #pragma unroll
;       for (int n = 0; n < 2; ++n) {
;         gp[m][n][0] = pack2(sigmoid_fast(g[m][n][0]), sigmoid_fast(g[m][n][1]));
;         gp[m][n][1] = pack2(sigmoid_fast(g[m][n][2]), sigmoid_fast(g[m][n][3]));
;       }
	s_addc_u32 s13, s71, s13
	global_load_lds_dwordx4 v[72:73], off
	v_lshl_add_u64 v[74:75], v[72:73], 0, s[8:9]
	s_mov_b32 m0, s1
	v_readfirstlane_b32 s1, v116
	v_lshl_add_u64 v[70:71], s[12:13], 0, v[98:99]
	global_load_lds_dwordx4 v[74:75], off
	s_mov_b32 m0, s1
	v_readfirstlane_b32 s1, v117
	global_load_lds_dwordx4 v[70:71], off
	v_lshl_add_u64 v[74:75], v[70:71], 0, s[8:9]
	s_mov_b32 m0, s1
	v_add_f32_e32 v0, 1.0, v0
	global_load_lds_dwordx4 v[74:75], off
	v_add_f32_e32 v74, 1.0, v76
	v_mul_f32_e32 v75, 0xbfb8aa3b, v136
	v_mul_f32_e32 v76, 0xbfb8aa3b, v137
	v_rcp_f32_e32 v0, v0
	v_rcp_f32_e32 v74, v74
	v_exp_f32_e32 v75, v75
	v_exp_f32_e32 v76, v76
	v_mul_f32_e32 v77, 0xbfb8aa3b, v155
	v_cvt_pk_bf16_f32 v74, v0, v74
	v_add_f32_e32 v0, 1.0, v75
	v_add_f32_e32 v75, 1.0, v76
	v_mul_f32_e32 v76, 0xbfb8aa3b, v154
	v_rcp_f32_e32 v0, v0
	v_rcp_f32_e32 v75, v75
	v_exp_f32_e32 v76, v76
	v_exp_f32_e32 v77, v77
	v_mul_f32_e32 v78, 0xbfb8aa3b, v157
	v_cvt_pk_bf16_f32 v75, v0, v75
	v_add_f32_e32 v0, 1.0, v76
	v_add_f32_e32 v76, 1.0, v77
	v_mul_f32_e32 v77, 0xbfb8aa3b, v156
	v_rcp_f32_e32 v0, v0
	v_rcp_f32_e32 v76, v76
	v_exp_f32_e32 v77, v77
	v_exp_f32_e32 v78, v78
	v_mul_f32_e32 v79, 0xbfb8aa3b, v159
	v_cvt_pk_bf16_f32 v76, v0, v76
	v_add_f32_e32 v0, 1.0, v77
	v_add_f32_e32 v77, 1.0, v78
	v_mul_f32_e32 v78, 0xbfb8aa3b, v158
	v_rcp_f32_e32 v0, v0
	v_rcp_f32_e32 v77, v77
	v_exp_f32_e32 v78, v78
	v_exp_f32_e32 v79, v79
	v_mul_f32_e32 v80, 0xbfb8aa3b, v161
	v_cvt_pk_bf16_f32 v77, v0, v77
	v_add_f32_e32 v0, 1.0, v78
	v_add_f32_e32 v78, 1.0, v79
	v_mul_f32_e32 v79, 0xbfb8aa3b, v160
	v_rcp_f32_e32 v0, v0
	v_rcp_f32_e32 v78, v78
	v_exp_f32_e32 v79, v79
	v_exp_f32_e32 v80, v80
	v_mul_f32_e32 v81, 0xbfb8aa3b, v163
	v_cvt_pk_bf16_f32 v78, v0, v78
	v_add_f32_e32 v0, 1.0, v79
	v_add_f32_e32 v79, 1.0, v80
	v_mul_f32_e32 v80, 0xbfb8aa3b, v162
	v_rcp_f32_e32 v0, v0
	v_rcp_f32_e32 v79, v79
	v_exp_f32_e32 v80, v80
	v_exp_f32_e32 v81, v81
	v_mul_f32_e32 v82, 0xbfb8aa3b, v165
	v_cvt_pk_bf16_f32 v79, v0, v79
	v_add_f32_e32 v0, 1.0, v80
	v_add_f32_e32 v80, 1.0, v81
	v_mul_f32_e32 v81, 0xbfb8aa3b, v164
	v_rcp_f32_e32 v0, v0
	v_rcp_f32_e32 v80, v80
	v_exp_f32_e32 v81, v81
	v_exp_f32_e32 v82, v82
	v_mul_f32_e32 v83, 0xbfb8aa3b, v197
	v_cvt_pk_bf16_f32 v80, v0, v80
	v_add_f32_e32 v0, 1.0, v81
	v_add_f32_e32 v81, 1.0, v82
	v_mul_f32_e32 v82, 0xbfb8aa3b, v196
	v_rcp_f32_e32 v0, v0
	v_rcp_f32_e32 v81, v81
	v_exp_f32_e32 v82, v82
	v_exp_f32_e32 v83, v83
	v_mul_f32_e32 v84, 0xbfb8aa3b, v199
	v_cvt_pk_bf16_f32 v81, v0, v81
	v_add_f32_e32 v0, 1.0, v82
	v_add_f32_e32 v82, 1.0, v83
	v_mul_f32_e32 v83, 0xbfb8aa3b, v198
	v_rcp_f32_e32 v0, v0
	v_rcp_f32_e32 v82, v82
	v_exp_f32_e32 v83, v83
	v_exp_f32_e32 v84, v84
	v_mul_f32_e32 v85, 0xbfb8aa3b, v201
	v_cvt_pk_bf16_f32 v82, v0, v82
	v_add_f32_e32 v0, 1.0, v83
	v_add_f32_e32 v83, 1.0, v84
	v_mul_f32_e32 v84, 0xbfb8aa3b, v200
	v_rcp_f32_e32 v0, v0
	v_rcp_f32_e32 v83, v83
	v_exp_f32_e32 v84, v84
	v_exp_f32_e32 v85, v85
	v_mul_f32_e32 v86, 0xbfb8aa3b, v203
	v_cvt_pk_bf16_f32 v83, v0, v83
	v_add_f32_e32 v0, 1.0, v84
	v_add_f32_e32 v84, 1.0, v85
	v_mul_f32_e32 v85, 0xbfb8aa3b, v202
	v_rcp_f32_e32 v0, v0
	v_rcp_f32_e32 v84, v84
	v_exp_f32_e32 v85, v85
	v_exp_f32_e32 v86, v86
	v_mul_f32_e32 v66, 0xbfb8aa3b, v66
	v_cvt_pk_bf16_f32 v84, v0, v84
	v_add_f32_e32 v0, 1.0, v85
	v_add_f32_e32 v85, 1.0, v86
	v_mul_f32_e32 v86, 0xbfb8aa3b, v204
	v_exp_f32_e32 v87, v86
	v_mul_f32_e32 v86, 0xbfb8aa3b, v205
	v_rcp_f32_e32 v0, v0
	v_rcp_f32_e32 v85, v85
	v_exp_f32_e32 v88, v86
	v_mul_f32_e32 v67, 0xbfb8aa3b, v67
	v_exp_f32_e32 v66, v66
	v_cvt_pk_bf16_f32 v86, v0, v85
	v_add_f32_e32 v0, 1.0, v87
	v_add_f32_e32 v85, 1.0, v88
	v_mul_f32_e32 v87, 0xbfb8aa3b, v206
	v_mul_f32_e32 v88, 0xbfb8aa3b, v207
	v_rcp_f32_e32 v0, v0
	v_rcp_f32_e32 v85, v85
	v_exp_f32_e32 v87, v87
	v_exp_f32_e32 v88, v88
	v_exp_f32_e32 v67, v67
	v_cvt_pk_bf16_f32 v89, v0, v85
	v_add_f32_e32 v0, 1.0, v87
	v_add_f32_e32 v85, 1.0, v88
	v_rcp_f32_e32 v0, v0
	v_rcp_f32_e32 v85, v85
	v_mul_f32_e32 v62, 0xbfb8aa3b, v62
	v_mul_f32_e32 v63, 0xbfb8aa3b, v63
	v_exp_f32_e32 v62, v62
	v_cvt_pk_bf16_f32 v92, v0, v85
	v_add_f32_e32 v0, 1.0, v66
	v_add_f32_e32 v66, 1.0, v67
	v_mul_f32_e32 v67, 0xbfb8aa3b, v68
	v_mul_f32_e32 v68, 0xbfb8aa3b, v69
	v_rcp_f32_e32 v0, v0
	v_rcp_f32_e32 v66, v66
	v_exp_f32_e32 v67, v67
	v_exp_f32_e32 v68, v68
	v_exp_f32_e32 v63, v63
	v_cvt_pk_bf16_f32 v96, v0, v66
	v_add_f32_e32 v0, 1.0, v67
	v_add_f32_e32 v66, 1.0, v68
	v_rcp_f32_e32 v0, v0
	v_rcp_f32_e32 v66, v66
	v_mul_f32_e32 v58, 0xbfb8aa3b, v58
	v_mul_f32_e32 v59, 0xbfb8aa3b, v59
	v_exp_f32_e32 v58, v58
	v_cvt_pk_bf16_f32 v110, v0, v66
	v_add_f32_e32 v0, 1.0, v62
	v_add_f32_e32 v62, 1.0, v63
	v_mul_f32_e32 v63, 0xbfb8aa3b, v64
	v_mul_f32_e32 v64, 0xbfb8aa3b, v65
	v_rcp_f32_e32 v0, v0
	v_rcp_f32_e32 v62, v62
	v_exp_f32_e32 v63, v63
	v_exp_f32_e32 v64, v64
	v_exp_f32_e32 v59, v59
	v_cvt_pk_bf16_f32 v113, v0, v62
	v_add_f32_e32 v0, 1.0, v63
	v_add_f32_e32 v62, 1.0, v64
	v_rcp_f32_e32 v0, v0
	v_rcp_f32_e32 v62, v62
	v_mul_f32_e32 v54, 0xbfb8aa3b, v54
	v_mul_f32_e32 v55, 0xbfb8aa3b, v55
	v_exp_f32_e32 v54, v54
	v_cvt_pk_bf16_f32 v134, v0, v62
	v_add_f32_e32 v0, 1.0, v58
	v_add_f32_e32 v58, 1.0, v59
	v_mul_f32_e32 v59, 0xbfb8aa3b, v60
	v_mul_f32_e32 v60, 0xbfb8aa3b, v61
	v_rcp_f32_e32 v0, v0
	v_rcp_f32_e32 v58, v58
	v_exp_f32_e32 v59, v59
	v_exp_f32_e32 v60, v60
	v_exp_f32_e32 v55, v55
	v_cvt_pk_bf16_f32 v135, v0, v58
	v_add_f32_e32 v0, 1.0, v59
	v_add_f32_e32 v58, 1.0, v60
	v_rcp_f32_e32 v0, v0
	v_rcp_f32_e32 v58, v58
	v_mul_f32_e32 v50, 0xbfb8aa3b, v50
	v_mul_f32_e32 v51, 0xbfb8aa3b, v51
	v_exp_f32_e32 v50, v50
; __device__ __forceinline__ float sigmoid_fast(float x) { return __builtin_amdgcn_rcpf(1.0f + __expf(-x)); }
; __device__ __forceinline__ void g4_phase(int zz, const Params& p, char* shm) {
;     ...
;     unsigned gp[12][2][2];
; #pragma unroll
;     for (int m = 0; m < 12; ++m)
; #pragma unroll
;       for (int n = 0; n < 2; ++n) {
;         gp[m][n][0] = pack2(sigmoid_fast(g[m][n][0]), sigmoid_fast(g[m][n][1]));
;         gp[m][n][1] = pack2(sigmoid_fast(g[m][n][2]), sigmoid_fast(g[m][n][3]));
;       }
	v_cvt_pk_bf16_f32 v136, v0, v58
	v_add_f32_e32 v0, 1.0, v54
	v_add_f32_e32 v54, 1.0, v55
	v_mul_f32_e32 v55, 0xbfb8aa3b, v56
	v_mul_f32_e32 v56, 0xbfb8aa3b, v57
	v_rcp_f32_e32 v0, v0
	v_rcp_f32_e32 v54, v54
	v_exp_f32_e32 v55, v55
	v_exp_f32_e32 v56, v56
	v_exp_f32_e32 v51, v51
	v_cvt_pk_bf16_f32 v137, v0, v54
	v_add_f32_e32 v0, 1.0, v55
	v_add_f32_e32 v54, 1.0, v56
	v_rcp_f32_e32 v0, v0
	v_rcp_f32_e32 v54, v54
	v_mul_f32_e32 v46, 0xbfb8aa3b, v46
	v_mul_f32_e32 v47, 0xbfb8aa3b, v47
	v_exp_f32_e32 v46, v46
	v_cvt_pk_bf16_f32 v138, v0, v54
	v_add_f32_e32 v0, 1.0, v50
	v_add_f32_e32 v50, 1.0, v51
	v_mul_f32_e32 v51, 0xbfb8aa3b, v52
	v_mul_f32_e32 v52, 0xbfb8aa3b, v53
	v_rcp_f32_e32 v0, v0
	v_rcp_f32_e32 v50, v50
	v_exp_f32_e32 v51, v51
	v_exp_f32_e32 v52, v52
	v_exp_f32_e32 v47, v47
	v_cvt_pk_bf16_f32 v139, v0, v50
	v_add_f32_e32 v0, 1.0, v51
	v_add_f32_e32 v50, 1.0, v52
	v_rcp_f32_e32 v0, v0
	v_rcp_f32_e32 v50, v50
	v_mul_f32_e32 v42, 0xbfb8aa3b, v42
	v_mul_f32_e32 v43, 0xbfb8aa3b, v43
	v_exp_f32_e32 v42, v42
	v_cvt_pk_bf16_f32 v141, v0, v50
	v_add_f32_e32 v0, 1.0, v46
	v_add_f32_e32 v46, 1.0, v47
	v_mul_f32_e32 v47, 0xbfb8aa3b, v48
	v_mul_f32_e32 v48, 0xbfb8aa3b, v49
	v_rcp_f32_e32 v0, v0
	v_rcp_f32_e32 v46, v46
	v_exp_f32_e32 v47, v47
	v_exp_f32_e32 v48, v48
	v_exp_f32_e32 v43, v43
	v_cvt_pk_bf16_f32 v143, v0, v46
	v_add_f32_e32 v0, 1.0, v47
	v_add_f32_e32 v46, 1.0, v48
	v_rcp_f32_e32 v0, v0
	v_rcp_f32_e32 v46, v46
	v_mul_f32_e32 v38, 0xbfb8aa3b, v38
	v_mul_f32_e32 v39, 0xbfb8aa3b, v39
	v_exp_f32_e32 v38, v38
	v_cvt_pk_bf16_f32 v144, v0, v46
	v_add_f32_e32 v0, 1.0, v42
	v_add_f32_e32 v42, 1.0, v43
	v_mul_f32_e32 v43, 0xbfb8aa3b, v44
	v_mul_f32_e32 v44, 0xbfb8aa3b, v45
	v_rcp_f32_e32 v0, v0
	v_rcp_f32_e32 v42, v42
	v_exp_f32_e32 v43, v43
	v_exp_f32_e32 v44, v44
	v_exp_f32_e32 v39, v39
	v_cvt_pk_bf16_f32 v145, v0, v42
	v_add_f32_e32 v0, 1.0, v43
	v_add_f32_e32 v42, 1.0, v44
	v_rcp_f32_e32 v0, v0
	v_rcp_f32_e32 v42, v42
	v_mul_f32_e32 v34, 0xbfb8aa3b, v34
	v_mul_f32_e32 v35, 0xbfb8aa3b, v35
	v_exp_f32_e32 v34, v34
	v_cvt_pk_bf16_f32 v146, v0, v42
	v_add_f32_e32 v0, 1.0, v38
	v_add_f32_e32 v38, 1.0, v39
	v_mul_f32_e32 v39, 0xbfb8aa3b, v40
	v_mul_f32_e32 v40, 0xbfb8aa3b, v41
	v_rcp_f32_e32 v0, v0
	v_rcp_f32_e32 v38, v38
	v_exp_f32_e32 v39, v39
	v_exp_f32_e32 v40, v40
	v_exp_f32_e32 v35, v35
	v_cvt_pk_bf16_f32 v147, v0, v38
	v_add_f32_e32 v0, 1.0, v39
	v_add_f32_e32 v38, 1.0, v40
	v_rcp_f32_e32 v0, v0
	v_rcp_f32_e32 v38, v38
	v_mul_f32_e32 v30, 0xbfb8aa3b, v30
	v_mul_f32_e32 v31, 0xbfb8aa3b, v31
	v_exp_f32_e32 v30, v30
	v_cvt_pk_bf16_f32 v148, v0, v38
	v_add_f32_e32 v0, 1.0, v34
	v_add_f32_e32 v34, 1.0, v35
	v_mul_f32_e32 v35, 0xbfb8aa3b, v36
	v_mul_f32_e32 v36, 0xbfb8aa3b, v37
	v_rcp_f32_e32 v0, v0
	v_rcp_f32_e32 v34, v34
	v_exp_f32_e32 v35, v35
	v_exp_f32_e32 v36, v36
	v_exp_f32_e32 v31, v31
	v_cvt_pk_bf16_f32 v149, v0, v34
	v_add_f32_e32 v0, 1.0, v35
	v_add_f32_e32 v34, 1.0, v36
	v_rcp_f32_e32 v0, v0
	v_rcp_f32_e32 v34, v34
	v_mul_f32_e32 v26, 0xbfb8aa3b, v26
	v_mul_f32_e32 v27, 0xbfb8aa3b, v27
	v_exp_f32_e32 v26, v26
	v_cvt_pk_bf16_f32 v150, v0, v34
	v_add_f32_e32 v0, 1.0, v30
	v_add_f32_e32 v30, 1.0, v31
	v_mul_f32_e32 v31, 0xbfb8aa3b, v32
	v_mul_f32_e32 v32, 0xbfb8aa3b, v33
	v_rcp_f32_e32 v0, v0
	v_rcp_f32_e32 v30, v30
	v_exp_f32_e32 v31, v31
	v_exp_f32_e32 v32, v32
	v_exp_f32_e32 v27, v27
	v_cvt_pk_bf16_f32 v85, v0, v30
	v_add_f32_e32 v0, 1.0, v31
	v_add_f32_e32 v30, 1.0, v32
	v_rcp_f32_e32 v0, v0
	v_rcp_f32_e32 v30, v30
	v_mul_f32_e32 v22, 0xbfb8aa3b, v22
	v_mul_f32_e32 v23, 0xbfb8aa3b, v23
	v_exp_f32_e32 v22, v22
	v_cvt_pk_bf16_f32 v87, v0, v30
	v_add_f32_e32 v0, 1.0, v26
	v_add_f32_e32 v26, 1.0, v27
	v_mul_f32_e32 v27, 0xbfb8aa3b, v28
	v_mul_f32_e32 v28, 0xbfb8aa3b, v29
	v_rcp_f32_e32 v0, v0
	v_rcp_f32_e32 v26, v26
	v_exp_f32_e32 v27, v27
	v_exp_f32_e32 v28, v28
	v_exp_f32_e32 v23, v23
	v_cvt_pk_bf16_f32 v88, v0, v26
	v_add_f32_e32 v0, 1.0, v27
	v_add_f32_e32 v26, 1.0, v28
	v_rcp_f32_e32 v0, v0
	v_rcp_f32_e32 v26, v26
	v_mul_f32_e32 v18, 0xbfb8aa3b, v18
	v_mul_f32_e32 v19, 0xbfb8aa3b, v19
	v_exp_f32_e32 v18, v18
	v_cvt_pk_bf16_f32 v90, v0, v26
	v_add_f32_e32 v0, 1.0, v22
	v_add_f32_e32 v22, 1.0, v23
	v_mul_f32_e32 v23, 0xbfb8aa3b, v24
	v_mul_f32_e32 v24, 0xbfb8aa3b, v25
	v_rcp_f32_e32 v0, v0
	v_rcp_f32_e32 v22, v22
	v_exp_f32_e32 v23, v23
	v_exp_f32_e32 v24, v24
	v_exp_f32_e32 v19, v19
	v_cvt_pk_bf16_f32 v91, v0, v22
	v_add_f32_e32 v0, 1.0, v23
	v_add_f32_e32 v22, 1.0, v24
	v_rcp_f32_e32 v0, v0
	v_rcp_f32_e32 v22, v22
	v_mul_f32_e32 v14, 0xbfb8aa3b, v14
	v_mul_f32_e32 v15, 0xbfb8aa3b, v15
	v_exp_f32_e32 v14, v14
	v_cvt_pk_bf16_f32 v93, v0, v22
	v_add_f32_e32 v0, 1.0, v18
	v_add_f32_e32 v18, 1.0, v19
	v_mul_f32_e32 v19, 0xbfb8aa3b, v20
	v_mul_f32_e32 v20, 0xbfb8aa3b, v21
	v_rcp_f32_e32 v0, v0
	v_rcp_f32_e32 v18, v18
	v_exp_f32_e32 v19, v19
; __device__ __forceinline__ float sigmoid_fast(float x) { return __builtin_amdgcn_rcpf(1.0f + __expf(-x)); }
; template <int MF, int NF>
; __device__ __forceinline__ void gemm_deep_branches(int zz, f32x4 (&mg)[MF][NF], const unsigned (&gp)[12][2][2], const u16* __restrict__ Wt, int ldw,
;                                           const u16* __restrict__ Act, int lda, int K, char* shm) {
;     ...
;   if (nt > 1) {
; #pragma unroll
;     for (int i = 0; i < NLD; ++i) {
;       const u16* src = (i < NLA) ? (Wt + (long)(i * 64) * ldw + 64 + voffA) : (Act + (long)((i - NLA) * 64) * lda + 64 + voffB);
;       __builtin_amdgcn_global_load_lds((const unsigned*)src, (unsigned*)(shm + 1 * STAGE_B + (i * 8 + wid) * 1024), 16, 0, 0);
;     }
;   }
;   if (nt > 2) {
; #pragma unroll
;     for (int i = 0; i < NLD; ++i) {
;       const u16* src = (i < NLA) ? (Wt + (long)(i * 64) * ldw + 128 + voffA) : (Act + (long)((i - NLA) * 64) * lda + 128 + voffB);
;       __builtin_amdgcn_global_load_lds((const unsigned*)src, (unsigned*)(shm + 2 * STAGE_B + (i * 8 + wid) * 1024), 16, 0, 0);
;     }
;   }
; __device__ __forceinline__ void g4_phase(int zz, const Params& p, char* shm) {
;     ...
;     unsigned gp[12][2][2];
; #pragma unroll
;     for (int m = 0; m < 12; ++m)
; #pragma unroll
;       for (int n = 0; n < 2; ++n) {
;         gp[m][n][0] = pack2(sigmoid_fast(g[m][n][0]), sigmoid_fast(g[m][n][1]));
;         gp[m][n][1] = pack2(sigmoid_fast(g[m][n][2]), sigmoid_fast(g[m][n][3]));
;       }
;     f32x4 mg[4][2];
; #pragma unroll
;     for (int m = 0; m < 4; ++m)
; #pragma unroll
;       for (int n = 0; n < 2; ++n) mg[m][n] = f32x4{0.f, 0.f, 0.f, 0.f};
	v_exp_f32_e32 v20, v20
	v_exp_f32_e32 v15, v15
	v_cvt_pk_bf16_f32 v94, v0, v18
	v_add_f32_e32 v0, 1.0, v19
	v_add_f32_e32 v18, 1.0, v20
	v_rcp_f32_e32 v0, v0
	v_rcp_f32_e32 v18, v18
	v_mul_f32_e32 v10, 0xbfb8aa3b, v10
	v_mul_f32_e32 v11, 0xbfb8aa3b, v11
	v_exp_f32_e32 v10, v10
	v_cvt_pk_bf16_f32 v95, v0, v18
	v_add_f32_e32 v0, 1.0, v14
	v_add_f32_e32 v14, 1.0, v15
	v_mul_f32_e32 v15, 0xbfb8aa3b, v16
	v_mul_f32_e32 v16, 0xbfb8aa3b, v17
	v_rcp_f32_e32 v0, v0
	v_rcp_f32_e32 v14, v14
	v_exp_f32_e32 v15, v15
	v_exp_f32_e32 v16, v16
	v_exp_f32_e32 v11, v11
	v_cvt_pk_bf16_f32 v97, v0, v14
	v_add_f32_e32 v0, 1.0, v15
	v_add_f32_e32 v14, 1.0, v16
	v_mul_f32_e32 v6, 0xbfb8aa3b, v6
	v_rcp_f32_e32 v0, v0
	v_rcp_f32_e32 v14, v14
	v_add_f32_e32 v10, 1.0, v10
	v_add_f32_e32 v11, 1.0, v11
	v_exp_f32_e32 v6, v6
	v_rcp_f32_e32 v10, v10
	v_rcp_f32_e32 v11, v11
	v_cvt_pk_bf16_f32 v133, v0, v14
	v_add_f32_e32 v0, 1.0, v6
	v_mul_f32_e32 v6, 0xbfb8aa3b, v7
	v_readfirstlane_b32 s1, v118
	v_cvt_pk_bf16_f32 v112, v10, v11
	v_exp_f32_e32 v10, v6
	v_lshl_add_u64 v[6:7], v[72:73], 0, s[90:91]
	s_mov_b32 m0, s1
	v_readfirstlane_b32 s1, v119
	global_load_lds_dwordx4 v[6:7], off
	v_lshl_add_u64 v[6:7], v[72:73], 0, s[92:93]
	s_mov_b32 m0, s1
	v_readfirstlane_b32 s1, v120
	global_load_lds_dwordx4 v[6:7], off
	v_lshl_add_u64 v[6:7], v[70:71], 0, s[90:91]
	s_mov_b32 m0, s1
	v_readfirstlane_b32 s1, v121
	v_add_u32_e32 v11, 0x10000, v114
	global_load_lds_dwordx4 v[6:7], off
	v_lshl_add_u64 v[6:7], v[70:71], 0, s[92:93]
	s_mov_b32 m0, s1
	s_mov_b64 s[8:9], 0x100
	v_readfirstlane_b32 s1, v11
	v_add_u32_e32 v11, 0x12000, v114
	global_load_lds_dwordx4 v[6:7], off
	v_lshl_add_u64 v[6:7], v[72:73], 0, s[8:9]
	s_mov_b32 m0, s1
	s_mov_b64 s[12:13], 0x20100
	v_readfirstlane_b32 s1, v11
	v_add_u32_e32 v11, 0x14000, v114
	global_load_lds_dwordx4 v[6:7], off
	v_lshl_add_u64 v[6:7], v[72:73], 0, s[12:13]
	s_mov_b32 m0, s1
	v_readfirstlane_b32 s1, v11
	v_add_u32_e32 v11, 0x16000, v114
	global_load_lds_dwordx4 v[6:7], off
	v_lshl_add_u64 v[6:7], v[70:71], 0, s[8:9]
	s_mov_b32 m0, s1
	v_readfirstlane_b32 s1, v11
	global_load_lds_dwordx4 v[6:7], off
	v_lshl_add_u64 v[6:7], v[70:71], 0, s[12:13]
	s_mov_b32 m0, s1
	v_mul_f32_e32 v2, 0xbfb8aa3b, v2
	global_load_lds_dwordx4 v[6:7], off
	v_mul_f32_e32 v3, 0xbfb8aa3b, v3
	v_mul_f32_e32 v12, 0xbfb8aa3b, v12
	v_mul_f32_e32 v13, 0xbfb8aa3b, v13
	v_mul_f32_e32 v7, 0xbfb8aa3b, v8
	v_mul_f32_e32 v8, 0xbfb8aa3b, v9
	v_exp_f32_e32 v2, v2
	v_exp_f32_e32 v3, v3
	v_mul_f32_e32 v4, 0xbfb8aa3b, v4
	v_mul_f32_e32 v5, 0xbfb8aa3b, v5
	v_exp_f32_e32 v12, v12
	v_exp_f32_e32 v13, v13
	v_exp_f32_e32 v7, v7
	v_exp_f32_e32 v8, v8
	v_exp_f32_e32 v4, v4
	v_exp_f32_e32 v5, v5
	v_add_f32_e32 v2, 1.0, v2
	v_add_f32_e32 v3, 1.0, v3
	v_add_f32_e32 v12, 1.0, v12
	v_add_f32_e32 v13, 1.0, v13
	v_add_f32_e32 v6, 1.0, v10
	v_add_f32_e32 v7, 1.0, v7
	v_add_f32_e32 v8, 1.0, v8
	v_rcp_f32_e32 v2, v2
	v_rcp_f32_e32 v3, v3
	v_add_f32_e32 v4, 1.0, v4
	v_add_f32_e32 v5, 1.0, v5
	v_rcp_f32_e32 v12, v12
	v_rcp_f32_e32 v13, v13
	v_rcp_f32_e32 v0, v0
	v_rcp_f32_e32 v6, v6
	v_rcp_f32_e32 v7, v7
	v_rcp_f32_e32 v8, v8
	v_rcp_f32_e32 v4, v4
	v_rcp_f32_e32 v5, v5
	v_cvt_pk_bf16_f32 v73, v2, v3
	v_mov_b32_e32 v2, v1
	v_mov_b32_e32 v3, v1
	v_cvt_pk_bf16_f32 v111, v12, v13
	v_cvt_pk_bf16_f32 v142, v0, v6
	v_cvt_pk_bf16_f32 v140, v7, v8
	v_cvt_pk_bf16_f32 v72, v4, v5
	v_mov_b32_e32 v0, v1
	v_mov_b32_e32 v36, 0
	v_mov_b64_e32 v[6:7], v[2:3]
	v_mov_b64_e32 v[10:11], v[2:3]
	v_mov_b64_e32 v[14:15], v[2:3]
	v_mov_b64_e32 v[18:19], v[2:3]
	v_mov_b64_e32 v[22:23], v[2:3]
	v_mov_b64_e32 v[26:27], v[2:3]
	v_mov_b64_e32 v[30:31], v[2:3]
	v_mov_b64_e32 v[34:35], v[2:3]
	v_lshl_add_u64 v[68:69], v[104:105], 0, s[6:7]
	v_lshl_add_u64 v[70:71], v[108:109], 0, s[4:5]
	s_mov_b32 s1, 0
	s_mov_b64 s[4:5], 0
	v_mov_b64_e32 v[4:5], v[0:1]
	v_mov_b64_e32 v[8:9], v[0:1]
	v_mov_b64_e32 v[12:13], v[0:1]
	v_mov_b64_e32 v[16:17], v[0:1]
	v_mov_b64_e32 v[20:21], v[0:1]
	v_mov_b64_e32 v[24:25], v[0:1]
	v_mov_b64_e32 v[28:29], v[0:1]
	v_mov_b64_e32 v[32:33], v[0:1]
	s_mov_b32 s3, 0
	v_mov_b32_e32 v37, v36
	v_mov_b32_e32 v38, v36
	v_mov_b32_e32 v39, v36
	v_mov_b32_e32 v64, v36
	v_mov_b32_e32 v65, v36
	v_mov_b32_e32 v66, v36
	v_mov_b32_e32 v67, v36
	v_mov_b32_e32 v60, v36
	v_mov_b32_e32 v61, v36
	v_mov_b32_e32 v62, v36
	v_mov_b32_e32 v63, v36
	v_mov_b32_e32 v56, v36
	v_mov_b32_e32 v57, v36
	v_mov_b32_e32 v58, v36
	v_mov_b32_e32 v59, v36
	v_mov_b32_e32 v52, v36
	v_mov_b32_e32 v53, v36
	v_mov_b32_e32 v54, v36
	v_mov_b32_e32 v55, v36
	v_mov_b32_e32 v48, v36
	v_mov_b32_e32 v49, v36
	v_mov_b32_e32 v50, v36
	v_mov_b32_e32 v51, v36
	v_mov_b32_e32 v44, v36
	v_mov_b32_e32 v45, v36
	v_mov_b32_e32 v46, v36
	v_mov_b32_e32 v47, v36
	v_mov_b32_e32 v40, v36
	v_mov_b32_e32 v41, v36
	v_mov_b32_e32 v42, v36
	v_mov_b32_e32 v43, v36
	s_branch .LBB0_759

; template <int MF, int NF>
; __device__ __forceinline__ void gemm_deep_branches(int zz, f32x4 (&mg)[MF][NF], const unsigned (&gp)[12][2][2], const u16* __restrict__ Wt, int ldw,
;                                           const u16* __restrict__ Act, int lda, int K, char* shm) {
;     ...
;   for (int t = 0; t < nt; ++t) {
;     const int cur = t & 3;
;     if (t + 2 < nt) asm volatile("s_waitcnt vmcnt(8)" ::: "memory");
;     else if (t + 1 < nt) asm volatile("s_waitcnt vmcnt(4)" ::: "memory");
;     else asm volatile("s_waitcnt vmcnt(0)" ::: "memory");
;     __builtin_amdgcn_s_barrier();
;     if (t + 3 < nt) {
; #pragma unroll
;       for (int i = 0; i < NLD; ++i) {
;         const u16* src = (i < NLA) ? (Wt + (long)(i * 64) * ldw + (t + 3) * 64 + voffA)
;                                    : (Act + (long)((i - NLA) * 64) * lda + (t + 3) * 64 + voffB);
;         __builtin_amdgcn_global_load_lds((const unsigned*)src, (unsigned*)(shm + ((t + 3) & 3) * STAGE_B + (i * 8 + wid) * 1024), 16, 0, 0);
;       }
;     }
;     const char* sbase = shm + cur * STAGE_B;
;     {
;       constexpr int D = 4, RING = D + 1, NSTEP = 2 * MF;
;       bf16x8 Bf[2][NF], Ar[RING];
; #pragma unroll
;       for (int n = 0; n < NF; ++n) Bf[0][n] = *(const bf16x8*)(sbase + boff + (n * 2 + 0) * 1024);
; #pragma unroll
;       for (int j = 0; j < D; ++j) Ar[j % RING] = *(const bf16x8*)(sbase + aoff + ((j % MF) * 2 + (j / MF)) * 1024);
;       __builtin_amdgcn_sched_barrier(0);
;       __builtin_amdgcn_s_setprio(1);
; #pragma unroll
;       for (int i = 0; i < NSTEP; ++i) {
;         const int ks = i / MF, m = i % MF;
;         const int j = i + D;
;         if (j < NSTEP) {
;           const int ksj = j / MF, mj = j % MF;
;           if (mj == 0) {
; #pragma unroll
;             for (int n = 0; n < NF; ++n) Bf[ksj][n] = *(const bf16x8*)(sbase + boff + (n * 2 + ksj) * 1024);
;           }
;           Ar[j % RING] = *(const bf16x8*)(sbase + aoff + (mj * 2 + ksj) * 1024);
;         }
; #pragma unroll
;         for (int n = 0; n < NF; ++n) acc[m][n] = __builtin_amdgcn_mfma_f32_16x16x32_bf16(Ar[i % RING], Bf[ks][n], acc[m][n], 0, 0, 0);
;         __builtin_amdgcn_sched_barrier(0);
;       }
;       __builtin_amdgcn_s_setprio(0);
;     }
.LBB0_759:
	s_add_i32 s6, s1, 0x18000
	s_and_b32 s6, s6, 0x18000
	v_add_u32_e32 v0, s6, v114
	v_lshl_add_u64 v[220:221], v[70:71], 0, s[4:5]
	s_mov_b64 s[6:7], 0x180
	v_lshl_add_u64 v[218:219], v[220:221], 0, s[6:7]
	v_lshl_add_u64 v[216:217], v[68:69], 0, s[4:5]
	s_mov_b64 s[6:7], 0x2200180
	v_lshl_add_u64 v[214:215], v[216:217], 0, s[6:7]
	v_readfirstlane_b32 s6, v0
	s_mov_b32 m0, s6
	s_mov_b64 s[6:7], 0x2220180
	v_lshl_add_u64 v[216:217], v[216:217], 0, s[6:7]
	s_mov_b64 s[6:7], 0x20180
	v_lshl_add_u64 v[220:221], v[220:221], 0, s[6:7]
	s_waitcnt vmcnt(8)
	s_barrier
	s_and_b32 s6, s1, 0x18000
	v_or_b32_e32 v0, s6, v126
	v_add_u32_e32 v2, s6, v125
	ds_read_b128 v[152:155], v0 offset:16384
	ds_read_b128 v[156:159], v0 offset:18432
	ds_read_b128 v[160:163], v2
	ds_read_b128 v[164:167], v2 offset:2048
	ds_read_b128 v[168:171], v2 offset:4096
	ds_read_b128 v[172:175], v2 offset:6144
	ds_read_b128 v[176:179], v0 offset:17408
	ds_read_b128 v[192:195], v0 offset:19456
	ds_read_b128 v[196:199], v2 offset:1024
	s_waitcnt lgkmcnt(6)
	v_mfma_f32_16x16x32_bf16 v[40:43], v[160:163], v[152:155], v[40:43]
	v_mfma_f32_16x16x32_bf16 v[44:47], v[160:163], v[156:159], v[44:47]
	global_load_lds_dwordx4 v[214:215], off
	s_waitcnt lgkmcnt(5)
	v_mfma_f32_16x16x32_bf16 v[48:51], v[164:167], v[152:155], v[48:51]
	s_addk_i32 m0, 0x2000
	ds_read_b128 v[160:163], v2 offset:3072
	v_mfma_f32_16x16x32_bf16 v[52:55], v[164:167], v[156:159], v[52:55]
	s_waitcnt lgkmcnt(5)
	v_mfma_f32_16x16x32_bf16 v[56:59], v[168:171], v[152:155], v[56:59]
	global_load_lds_dwordx4 v[216:217], off
	ds_read_b128 v[164:167], v2 offset:5120
	v_mfma_f32_16x16x32_bf16 v[60:63], v[168:171], v[156:159], v[60:63]
	s_addk_i32 m0, 0x2000
	s_waitcnt lgkmcnt(5)
	v_mfma_f32_16x16x32_bf16 v[64:67], v[172:175], v[152:155], v[64:67]
	ds_read_b128 v[152:155], v2 offset:7168
	v_mfma_f32_16x16x32_bf16 v[36:39], v[172:175], v[156:159], v[36:39]
	global_load_lds_dwordx4 v[218:219], off
	s_waitcnt lgkmcnt(3)
	v_mfma_f32_16x16x32_bf16 v[40:43], v[196:199], v[176:179], v[40:43]
	s_addk_i32 m0, 0x2000
	v_mfma_f32_16x16x32_bf16 v[44:47], v[196:199], v[192:195], v[44:47]
	s_waitcnt lgkmcnt(2)
	v_mfma_f32_16x16x32_bf16 v[48:51], v[160:163], v[176:179], v[48:51]
	global_load_lds_dwordx4 v[220:221], off
	v_mfma_f32_16x16x32_bf16 v[52:55], v[160:163], v[192:195], v[52:55]
	s_waitcnt lgkmcnt(1)
	v_mfma_f32_16x16x32_bf16 v[56:59], v[164:167], v[176:179], v[56:59]
	v_mfma_f32_16x16x32_bf16 v[60:63], v[164:167], v[192:195], v[60:63]
	s_waitcnt lgkmcnt(0)
	v_mfma_f32_16x16x32_bf16 v[64:67], v[152:155], v[176:179], v[64:67]
	v_mfma_f32_16x16x32_bf16 v[36:39], v[152:155], v[192:195], v[36:39]
	s_setprio 0
	s_cmp_lt_i32 s3, 11
	s_cbranch_scc1 .LBB0_762
	s_cmp_gt_i32 s3, 14
	s_cbranch_scc0 .LBB0_764
	s_cmp_eq_u32 s3, 15
	s_cselect_b64 s[6:7], -1, 0
	s_cbranch_execz .LBB0_765
	s_branch .LBB0_766
